# generic pipelined weight-transpose routine in the prologue phase
# baseline (speedup 1.0000x reference)
.LBB0_21:
	s_load_dwordx16 s[8:23], s[0:1], 0x40
	s_cmpk_gt_i32 s76, 0x1dff
	s_cbranch_scc1 .LBB0_55
	s_waitcnt lgkmcnt(0)
	v_and_b32_e32 v154, 63, v200
	v_lshrrev_b32_e32 v153, 3, v154
	v_and_b32_e32 v154, 7, v154
	v_lshlrev_b32_e32 v155, 2, v153
	s_lshl_b32 s0, s30, 14
	v_mul_u32_u24_e32 v152, 0x84, v153
	v_lshl_add_u32 v144, v154, 4, v152
	v_add_u32_e32 v144, s0, v144
	v_add_u32_e32 v145, 0x420, v144
	v_add_u32_e32 v146, 0x840, v144
	v_add_u32_e32 v147, 0xc60, v144
	v_add_u32_e32 v148, 0x1080, v144
	v_add_u32_e32 v149, 0x14a0, v144
	v_add_u32_e32 v150, 0x18c0, v144
	v_add_u32_e32 v151, 0x1ce0, v144
	v_mul_u32_u24_e32 v152, 0x420, v154
	v_lshl_add_u32 v152, v153, 2, v152
	v_add_u32_e32 v152, s0, v152
	v_lshlrev_b32_e32 v154, 4, v154
	s_mov_b32 s33, s76
	s_mov_b32 s31, s76
	s_cmp_lt_i32 s33, 1536
	s_cbranch_scc0 .Ltr_dla1
	s_sub_i32 s0, s33, 0
	s_mul_i32 s1, s0, 683
	s_lshr_b32 s1, s1, 16
	s_mul_i32 s4, s1, 96
	s_sub_i32 s0, s0, s4
	s_lshl_b32 s1, s1, 6
	s_lshl_b32 s0, s0, 5
	s_mul_i32 s4, s1, 3072
	s_add_i32 s4, s4, s0
	s_lshl_b32 s4, s4, 2
	v_readlane_b32 s26, v248, 8
	v_readlane_b32 s27, v248, 9
	s_nop 0
	s_add_u32 s34, s26, s4
	s_addc_u32 s35, s27, 0
	s_mov_b32 s36, 0x18000
	s_mov_b32 s37, 0x3000
	s_and_b32 s1, s1, 0x3ff
	s_lshl_b32 s1, s1, 2
	s_add_u32 s38, s18, s1
	s_addc_u32 s39, s19, 0
	s_branch .Ltr_dxla
.Ltr_dla1:
	s_cmp_lt_i32 s33, 2048
	s_cbranch_scc0 .Ltr_dla2
	s_sub_i32 s0, s33, 1536
	s_lshr_b32 s1, s0, 5
	s_and_b32 s0, s0, 31
	s_lshl_b32 s1, s1, 6
	s_lshl_b32 s0, s0, 5
	s_mul_i32 s4, s1, 1024
	s_add_i32 s4, s4, s0
	s_lshl_b32 s4, s4, 2
	v_readlane_b32 s26, v248, 16
	v_readlane_b32 s27, v248, 17
	s_nop 0
	s_add_u32 s34, s26, s4
	s_addc_u32 s35, s27, 0
	s_mov_b32 s36, 0x8000
	s_mov_b32 s37, 0x1000
	s_and_b32 s1, s1, 0x3ff
	s_lshl_b32 s1, s1, 2
	s_add_u32 s38, s18, s1
	s_addc_u32 s39, s19, 0
	s_branch .Ltr_dxla
.Ltr_dla2:
	s_cmp_lt_i32 s33, 3072
	s_cbranch_scc0 .Ltr_dla3
	s_sub_i32 s0, s33, 2048
	s_lshr_b32 s1, s0, 6
	s_and_b32 s0, s0, 63
	s_lshl_b32 s1, s1, 6
	s_lshl_b32 s0, s0, 5
	s_mul_i32 s4, s1, 2048
	s_add_i32 s4, s4, s0
	s_lshl_b32 s4, s4, 2
	s_add_u32 s34, s14, s4
	s_addc_u32 s35, s15, 0
	s_mov_b32 s36, 0x10000
	s_mov_b32 s37, 0x2000
	s_and_b32 s1, s1, 0x3ff
	s_lshl_b32 s1, s1, 2
	s_add_u32 s38, s18, s1
	s_addc_u32 s39, s19, 0
	s_branch .Ltr_dxla
.Ltr_dla3:
	s_cmp_lt_i32 s33, 3584
	s_cbranch_scc0 .Ltr_dla4
	s_sub_i32 s0, s33, 3072
	s_lshr_b32 s1, s0, 5
	s_and_b32 s0, s0, 31
	s_lshl_b32 s1, s1, 6
	s_lshl_b32 s0, s0, 5
	s_mul_i32 s4, s1, 1024
	s_add_i32 s4, s4, s0
	s_lshl_b32 s4, s4, 2
	s_add_u32 s34, s16, s4
	s_addc_u32 s35, s17, 0
	s_mov_b32 s36, 0x8000
	s_mov_b32 s37, 0x1000
	s_and_b32 s1, s1, 0x3ff
	s_lshl_b32 s1, s1, 2
	s_add_u32 s38, s18, s1
	s_addc_u32 s39, s19, 0
	s_branch .Ltr_dxla
.Ltr_dla4:
	s_cmp_lt_i32 s33, 5632
	s_cbranch_scc0 .Ltr_dla5
	s_sub_i32 s0, s33, 3584
	s_lshr_b32 s1, s0, 7
	s_and_b32 s0, s0, 127
	s_lshl_b32 s1, s1, 6
	s_lshl_b32 s0, s0, 5
	s_mul_i32 s4, s1, 4096
	s_add_i32 s4, s4, s0
	s_lshl_b32 s4, s4, 2
	s_add_u32 s34, s20, s4
	s_addc_u32 s35, s21, 0
	s_mov_b32 s36, 0x20000
	s_mov_b32 s37, 0x4000
	s_and_b32 s1, s1, 0x3ff
	s_lshl_b32 s1, s1, 2
	s_add_u32 s38, s18, s1
	s_addc_u32 s39, s19, 0
	s_branch .Ltr_dxla
.Ltr_dla5:
	s_sub_i32 s0, s33, 5632
	s_lshr_b32 s1, s0, 5
	s_and_b32 s0, s0, 31
	s_lshl_b32 s1, s1, 6
	s_lshl_b32 s0, s0, 5
	s_mul_i32 s4, s1, 1024
	s_add_i32 s4, s4, s0
	s_lshl_b32 s4, s4, 2
	s_add_u32 s34, s22, s4
	s_addc_u32 s35, s23, 0
	s_mov_b32 s36, 0x8000
	s_mov_b32 s37, 0x1000
	s_and_b32 s1, s1, 0x3ff
	s_lshl_b32 s1, s1, 2
	s_add_u32 s38, s18, s1
	s_addc_u32 s39, s19, 0
	s_branch .Ltr_dxla
.Ltr_dxla:
	v_mad_u32_u24 v156, v153, s37, v154
	global_load_dwordx4 v[64:67], v156, s[34:35] nt
	s_add_u32 s34, s34, s36
	s_addc_u32 s35, s35, 0
	global_load_dwordx4 v[68:71], v156, s[34:35] nt
	s_add_u32 s34, s34, s36
	s_addc_u32 s35, s35, 0
	global_load_dwordx4 v[72:75], v156, s[34:35] nt
	s_add_u32 s34, s34, s36
	s_addc_u32 s35, s35, 0
	global_load_dwordx4 v[76:79], v156, s[34:35] nt
	s_add_u32 s34, s34, s36
	s_addc_u32 s35, s35, 0
	global_load_dwordx4 v[80:83], v156, s[34:35] nt
	s_add_u32 s34, s34, s36
	s_addc_u32 s35, s35, 0
	global_load_dwordx4 v[84:87], v156, s[34:35] nt
	s_add_u32 s34, s34, s36
	s_addc_u32 s35, s35, 0
	global_load_dwordx4 v[88:91], v156, s[34:35] nt
	s_add_u32 s34, s34, s36
	s_addc_u32 s35, s35, 0
	global_load_dwordx4 v[92:95], v156, s[34:35] nt
	s_add_u32 s34, s34, s36
	s_addc_u32 s35, s35, 0
	global_load_dword v128, v155, s[38:39]
	global_load_dword v129, v155, s[38:39] offset:32
	global_load_dword v130, v155, s[38:39] offset:64
	global_load_dword v131, v155, s[38:39] offset:96
	global_load_dword v132, v155, s[38:39] offset:128
	global_load_dword v133, v155, s[38:39] offset:160
	global_load_dword v134, v155, s[38:39] offset:192
	global_load_dword v135, v155, s[38:39] offset:224
	s_add_i32 s33, s33, s78
	s_cmp_lt_i32 s33, 7680
	s_cbranch_scc0 .Ltr_f1
	s_cmp_lt_i32 s33, 1536
	s_cbranch_scc0 .Ltr_dlb1
	s_sub_i32 s0, s33, 0
	s_mul_i32 s1, s0, 683
	s_lshr_b32 s1, s1, 16
	s_mul_i32 s4, s1, 96
	s_sub_i32 s0, s0, s4
	s_lshl_b32 s1, s1, 6
	s_lshl_b32 s0, s0, 5
	s_mul_i32 s4, s1, 3072
	s_add_i32 s4, s4, s0
	s_lshl_b32 s4, s4, 2
	v_readlane_b32 s26, v248, 8
	v_readlane_b32 s27, v248, 9
	s_nop 0
	s_add_u32 s34, s26, s4
	s_addc_u32 s35, s27, 0
	s_mov_b32 s36, 0x18000
	s_mov_b32 s37, 0x3000
	s_and_b32 s1, s1, 0x3ff
	s_lshl_b32 s1, s1, 2
	s_add_u32 s38, s18, s1
	s_addc_u32 s39, s19, 0
	s_branch .Ltr_dxlb

.Ltr_dxlb:
	v_mad_u32_u24 v156, v153, s37, v154
	global_load_dwordx4 v[96:99], v156, s[34:35] nt
	s_add_u32 s34, s34, s36
	s_addc_u32 s35, s35, 0
	global_load_dwordx4 v[100:103], v156, s[34:35] nt
	s_add_u32 s34, s34, s36
	s_addc_u32 s35, s35, 0
	global_load_dwordx4 v[104:107], v156, s[34:35] nt
	s_add_u32 s34, s34, s36
	s_addc_u32 s35, s35, 0
	global_load_dwordx4 v[108:111], v156, s[34:35] nt
	s_add_u32 s34, s34, s36
	s_addc_u32 s35, s35, 0
	global_load_dwordx4 v[112:115], v156, s[34:35] nt
	s_add_u32 s34, s34, s36
	s_addc_u32 s35, s35, 0
	global_load_dwordx4 v[116:119], v156, s[34:35] nt
	s_add_u32 s34, s34, s36
	s_addc_u32 s35, s35, 0
	global_load_dwordx4 v[120:123], v156, s[34:35] nt
	s_add_u32 s34, s34, s36
	s_addc_u32 s35, s35, 0
	global_load_dwordx4 v[124:127], v156, s[34:35] nt
	s_add_u32 s34, s34, s36
	s_addc_u32 s35, s35, 0
	global_load_dword v136, v155, s[38:39]
	global_load_dword v137, v155, s[38:39] offset:32
	global_load_dword v138, v155, s[38:39] offset:64
	global_load_dword v139, v155, s[38:39] offset:96
	global_load_dword v140, v155, s[38:39] offset:128
	global_load_dword v141, v155, s[38:39] offset:160
	global_load_dword v142, v155, s[38:39] offset:192
	global_load_dword v143, v155, s[38:39] offset:224
	s_add_i32 s33, s33, s78
	s_waitcnt vmcnt(16)
	s_branch .Ltr_c0
.Ltr_f1:
	s_waitcnt vmcnt(0)
	s_branch .Ltr_c0
.Ltr_loop:
	s_add_i32 s0, s31, s78
	s_cmp_lt_i32 s0, 7680
	s_cbranch_scc1 .Ltr_w0
	s_waitcnt vmcnt(0)
	s_branch .Ltr_c0

.Ltr_c0:
	s_cmp_lt_i32 s31, 1536
	s_cbranch_scc0 .Ltr_dc01
	s_sub_i32 s0, s31, 0
	s_mul_i32 s1, s0, 683
	s_lshr_b32 s1, s1, 16
	s_mul_i32 s4, s1, 96
	s_sub_i32 s0, s0, s4
	s_lshl_b32 s1, s1, 6
	s_lshl_b32 s0, s0, 5
	s_mul_i32 s4, s0, 1024
	s_add_i32 s4, s4, s1
	s_lshl_b32 s4, s4, 1
	s_add_u32 s40, s88, s4
	s_addc_u32 s41, s89, 0
	s_add_u32 s40, s40, 0x100000
	s_addc_u32 s41, s41, 0
	s_mov_b32 s42, 0x4000
	s_mov_b32 s43, 0x800
	s_mov_b32 s44, 0
	s_branch .Ltr_dxc0
.Ltr_dc01:
	s_cmp_lt_i32 s31, 2048
	s_cbranch_scc0 .Ltr_dc02
	s_sub_i32 s0, s31, 1536
	s_lshr_b32 s1, s0, 5
	s_and_b32 s0, s0, 31
	s_lshl_b32 s1, s1, 6
	s_lshl_b32 s0, s0, 5
	s_mul_i32 s4, s0, 1024
	s_add_i32 s4, s4, s1
	s_lshl_b32 s4, s4, 1
	s_add_u32 s40, s88, s4
	s_addc_u32 s41, s89, 0
	s_add_u32 s40, s40, 0x700000
	s_addc_u32 s41, s41, 0
	s_mov_b32 s42, 0x4000
	s_mov_b32 s43, 0x800
	s_mov_b32 s44, 0
	s_branch .Ltr_dxc0
.Ltr_dc02:
	s_cmp_lt_i32 s31, 3072
	s_cbranch_scc0 .Ltr_dc03
	s_sub_i32 s0, s31, 2048
	s_lshr_b32 s1, s0, 6
	s_and_b32 s0, s0, 63
	s_lshl_b32 s1, s1, 6
	s_lshl_b32 s0, s0, 5
	s_mul_i32 s4, s0, 1024
	s_add_i32 s4, s4, s1
	s_lshl_b32 s4, s4, 1
	s_add_u32 s40, s88, s4
	s_addc_u32 s41, s89, 0
	s_add_u32 s40, s40, 0xb00000
	s_addc_u32 s41, s41, 0
	s_mov_b32 s42, 0x4000
	s_mov_b32 s43, 0x800
	s_mov_b32 s44, 0
	s_branch .Ltr_dxc0
.Ltr_dc03:
	s_cmp_lt_i32 s31, 3584
	s_cbranch_scc0 .Ltr_dc04
	s_sub_i32 s0, s31, 3072
	s_lshr_b32 s1, s0, 5
	s_and_b32 s0, s0, 31
	s_lshl_b32 s1, s1, 6
	s_lshl_b32 s0, s0, 5
	s_mul_i32 s4, s0, 1024
	s_add_i32 s4, s4, s1
	s_lshl_b32 s4, s4, 1
	s_add_u32 s40, s88, s4
	s_addc_u32 s41, s89, 0
	s_add_u32 s40, s40, 0xf00000
	s_addc_u32 s41, s41, 0
	s_mov_b32 s42, 0x4000
	s_mov_b32 s43, 0x800
	s_mov_b32 s44, 0
	s_branch .Ltr_dxc0
.Ltr_dc04:
	s_cmp_lt_i32 s31, 5632
	s_cbranch_scc0 .Ltr_dc05
	s_sub_i32 s0, s31, 3584
	s_lshr_b32 s1, s0, 7
	s_and_b32 s0, s0, 127
	s_lshl_b32 s1, s1, 6
	s_lshl_b32 s0, s0, 5
	s_mul_i32 s4, s0, 1024
	s_add_i32 s4, s4, s1
	s_lshl_b32 s4, s4, 1
	s_add_u32 s40, s88, s4
	s_addc_u32 s41, s89, 0
	s_add_u32 s40, s40, 0x1100000
	s_addc_u32 s41, s41, 0
	s_mov_b32 s42, 0x4000
	s_mov_b32 s43, 0x800
	s_mov_b32 s44, 1
	s_branch .Ltr_dxc0
.Ltr_dc05:
	s_sub_i32 s0, s31, 5632
	s_lshr_b32 s1, s0, 5
	s_and_b32 s0, s0, 31
	s_lshl_b32 s1, s1, 6
	s_lshl_b32 s0, s0, 5
	s_mul_i32 s4, s0, 4096
	s_add_i32 s4, s4, s1
	s_lshl_b32 s4, s4, 1
	s_add_u32 s40, s88, s4
	s_addc_u32 s41, s89, 0
	s_add_u32 s40, s40, 0x1900000
	s_addc_u32 s41, s41, 0
	s_mov_b32 s42, 0x10000
	s_mov_b32 s43, 0x2000
	s_mov_b32 s44, 0
	s_branch .Ltr_dxc0
.Ltr_dxc0:
	s_cmp_eq_u32 s44, 0
	s_cbranch_scc1 .Ltr_ngc0
	v_mul_f32_e32 v64, v64, v128
	v_mul_f32_e32 v65, v65, v128
	v_mul_f32_e32 v66, v66, v128
	v_mul_f32_e32 v67, v67, v128
	v_mul_f32_e32 v68, v68, v129
	v_mul_f32_e32 v69, v69, v129
	v_mul_f32_e32 v70, v70, v129
	v_mul_f32_e32 v71, v71, v129
	v_mul_f32_e32 v72, v72, v130
	v_mul_f32_e32 v73, v73, v130
	v_mul_f32_e32 v74, v74, v130
	v_mul_f32_e32 v75, v75, v130
	v_mul_f32_e32 v76, v76, v131
	v_mul_f32_e32 v77, v77, v131
	v_mul_f32_e32 v78, v78, v131
	v_mul_f32_e32 v79, v79, v131
	v_mul_f32_e32 v80, v80, v132
	v_mul_f32_e32 v81, v81, v132
	v_mul_f32_e32 v82, v82, v132
	v_mul_f32_e32 v83, v83, v132
	v_mul_f32_e32 v84, v84, v133
	v_mul_f32_e32 v85, v85, v133
	v_mul_f32_e32 v86, v86, v133
	v_mul_f32_e32 v87, v87, v133
	v_mul_f32_e32 v88, v88, v134
	v_mul_f32_e32 v89, v89, v134
	v_mul_f32_e32 v90, v90, v134
	v_mul_f32_e32 v91, v91, v134
	v_mul_f32_e32 v92, v92, v135
	v_mul_f32_e32 v93, v93, v135
	v_mul_f32_e32 v94, v94, v135
	v_mul_f32_e32 v95, v95, v135
.Ltr_ngc0:
	ds_write2_b32 v144, v64, v65 offset1:1
	ds_write2_b32 v144, v66, v67 offset0:2 offset1:3
	ds_write2_b32 v145, v68, v69 offset1:1
	ds_write2_b32 v145, v70, v71 offset0:2 offset1:3
	ds_write2_b32 v146, v72, v73 offset1:1
	ds_write2_b32 v146, v74, v75 offset0:2 offset1:3
	ds_write2_b32 v147, v76, v77 offset1:1
	ds_write2_b32 v147, v78, v79 offset0:2 offset1:3
	ds_write2_b32 v148, v80, v81 offset1:1
	ds_write2_b32 v148, v82, v83 offset0:2 offset1:3
	ds_write2_b32 v149, v84, v85 offset1:1
	ds_write2_b32 v149, v86, v87 offset0:2 offset1:3
	ds_write2_b32 v150, v88, v89 offset1:1
	ds_write2_b32 v150, v90, v91 offset0:2 offset1:3
	ds_write2_b32 v151, v92, v93 offset1:1
	ds_write2_b32 v151, v94, v95 offset0:2 offset1:3
	v_mad_u32_u24 v157, v153, s43, v154
	s_waitcnt lgkmcnt(0)
	ds_read2_b32 v[208:209], v152 offset0:0 offset1:8
	ds_read2_b32 v[210:211], v152 offset0:16 offset1:24
	ds_read2_b32 v[212:213], v152 offset0:33 offset1:41
	ds_read2_b32 v[214:215], v152 offset0:49 offset1:57
	ds_read2_b32 v[216:217], v152 offset0:66 offset1:74
	ds_read2_b32 v[218:219], v152 offset0:82 offset1:90
	ds_read2_b32 v[220:221], v152 offset0:99 offset1:107
	ds_read2_b32 v[222:223], v152 offset0:115 offset1:123
	ds_read2_b32 v[224:225], v152 offset0:132 offset1:140
	ds_read2_b32 v[226:227], v152 offset0:148 offset1:156
	ds_read2_b32 v[228:229], v152 offset0:165 offset1:173
	ds_read2_b32 v[230:231], v152 offset0:181 offset1:189
	ds_read2_b32 v[232:233], v152 offset0:198 offset1:206
	ds_read2_b32 v[234:235], v152 offset0:214 offset1:222
	ds_read2_b32 v[236:237], v152 offset0:231 offset1:239
	ds_read2_b32 v[238:239], v152 offset0:247 offset1:255
	s_waitcnt lgkmcnt(0)
	v_cvt_pk_bf16_f32 v160, v208, v212
	v_cvt_pk_bf16_f32 v161, v216, v220
	v_cvt_pk_bf16_f32 v162, v224, v228
	v_cvt_pk_bf16_f32 v163, v232, v236
	v_cvt_pk_bf16_f32 v164, v209, v213
	v_cvt_pk_bf16_f32 v165, v217, v221
	v_cvt_pk_bf16_f32 v166, v225, v229
	v_cvt_pk_bf16_f32 v167, v233, v237
	v_cvt_pk_bf16_f32 v168, v210, v214
	v_cvt_pk_bf16_f32 v169, v218, v222
	v_cvt_pk_bf16_f32 v170, v226, v230
	v_cvt_pk_bf16_f32 v171, v234, v238
	v_cvt_pk_bf16_f32 v172, v211, v215
	v_cvt_pk_bf16_f32 v173, v219, v223
	v_cvt_pk_bf16_f32 v174, v227, v231
	v_cvt_pk_bf16_f32 v175, v235, v239
	global_store_dwordx4 v157, v[160:163], s[40:41]
	s_add_u32 s40, s40, s42
	s_addc_u32 s41, s41, 0
	global_store_dwordx4 v157, v[164:167], s[40:41]
	s_add_u32 s40, s40, s42
	s_addc_u32 s41, s41, 0
	global_store_dwordx4 v157, v[168:171], s[40:41]
	s_add_u32 s40, s40, s42
	s_addc_u32 s41, s41, 0
	global_store_dwordx4 v157, v[172:175], s[40:41]
	s_add_u32 s40, s40, s42
	s_addc_u32 s41, s41, 0
	s_cmp_lt_i32 s33, 7680
	s_cbranch_scc0 .Ltr_nl0
	s_cmp_lt_i32 s33, 1536
	s_cbranch_scc0 .Ltr_dl01
	s_sub_i32 s0, s33, 0
	s_mul_i32 s1, s0, 683
	s_lshr_b32 s1, s1, 16
	s_mul_i32 s4, s1, 96
	s_sub_i32 s0, s0, s4
	s_lshl_b32 s1, s1, 6
	s_lshl_b32 s0, s0, 5
	s_mul_i32 s4, s1, 3072
	s_add_i32 s4, s4, s0
	s_lshl_b32 s4, s4, 2
	v_readlane_b32 s26, v248, 8
	v_readlane_b32 s27, v248, 9
	s_nop 0
	s_add_u32 s34, s26, s4
	s_addc_u32 s35, s27, 0
	s_mov_b32 s36, 0x18000
	s_mov_b32 s37, 0x3000
	s_and_b32 s1, s1, 0x3ff
	s_lshl_b32 s1, s1, 2
	s_add_u32 s38, s18, s1
	s_addc_u32 s39, s19, 0
	s_branch .Ltr_dxl0

.Ltr_dxl0:
	v_mad_u32_u24 v156, v153, s37, v154
	global_load_dwordx4 v[64:67], v156, s[34:35] nt
	s_add_u32 s34, s34, s36
	s_addc_u32 s35, s35, 0
	global_load_dwordx4 v[68:71], v156, s[34:35] nt
	s_add_u32 s34, s34, s36
	s_addc_u32 s35, s35, 0
	global_load_dwordx4 v[72:75], v156, s[34:35] nt
	s_add_u32 s34, s34, s36
	s_addc_u32 s35, s35, 0
	global_load_dwordx4 v[76:79], v156, s[34:35] nt
	s_add_u32 s34, s34, s36
	s_addc_u32 s35, s35, 0
	global_load_dwordx4 v[80:83], v156, s[34:35] nt
	s_add_u32 s34, s34, s36
	s_addc_u32 s35, s35, 0
	global_load_dwordx4 v[84:87], v156, s[34:35] nt
	s_add_u32 s34, s34, s36
	s_addc_u32 s35, s35, 0
	global_load_dwordx4 v[88:91], v156, s[34:35] nt
	s_add_u32 s34, s34, s36
	s_addc_u32 s35, s35, 0
	global_load_dwordx4 v[92:95], v156, s[34:35] nt
	s_add_u32 s34, s34, s36
	s_addc_u32 s35, s35, 0
	global_load_dword v128, v155, s[38:39]
	global_load_dword v129, v155, s[38:39] offset:32
	global_load_dword v130, v155, s[38:39] offset:64
	global_load_dword v131, v155, s[38:39] offset:96
	global_load_dword v132, v155, s[38:39] offset:128
	global_load_dword v133, v155, s[38:39] offset:160
	global_load_dword v134, v155, s[38:39] offset:192
	global_load_dword v135, v155, s[38:39] offset:224
	s_add_i32 s33, s33, s78
.Ltr_nl0:
	s_add_i32 s31, s31, s78
	s_cmp_lt_i32 s31, 7680
	s_cbranch_scc0 .LBB0_55
	s_add_i32 s0, s31, s78
	s_cmp_lt_i32 s0, 7680
	s_cbranch_scc1 .Ltr_w1
	s_waitcnt vmcnt(0)
	s_branch .Ltr_c1

.Ltr_dxc1:
	s_cmp_eq_u32 s44, 0
	s_cbranch_scc1 .Ltr_ngc1
	v_mul_f32_e32 v96, v96, v136
	v_mul_f32_e32 v97, v97, v136
	v_mul_f32_e32 v98, v98, v136
	v_mul_f32_e32 v99, v99, v136
	v_mul_f32_e32 v100, v100, v137
	v_mul_f32_e32 v101, v101, v137
	v_mul_f32_e32 v102, v102, v137
	v_mul_f32_e32 v103, v103, v137
	v_mul_f32_e32 v104, v104, v138
	v_mul_f32_e32 v105, v105, v138
	v_mul_f32_e32 v106, v106, v138
	v_mul_f32_e32 v107, v107, v138
	v_mul_f32_e32 v108, v108, v139
	v_mul_f32_e32 v109, v109, v139
	v_mul_f32_e32 v110, v110, v139
	v_mul_f32_e32 v111, v111, v139
	v_mul_f32_e32 v112, v112, v140
	v_mul_f32_e32 v113, v113, v140
	v_mul_f32_e32 v114, v114, v140
	v_mul_f32_e32 v115, v115, v140
	v_mul_f32_e32 v116, v116, v141
	v_mul_f32_e32 v117, v117, v141
	v_mul_f32_e32 v118, v118, v141
	v_mul_f32_e32 v119, v119, v141
	v_mul_f32_e32 v120, v120, v142
	v_mul_f32_e32 v121, v121, v142
	v_mul_f32_e32 v122, v122, v142
	v_mul_f32_e32 v123, v123, v142
	v_mul_f32_e32 v124, v124, v143
	v_mul_f32_e32 v125, v125, v143
	v_mul_f32_e32 v126, v126, v143
	v_mul_f32_e32 v127, v127, v143
.Ltr_ngc1:
	ds_write2_b32 v144, v96, v97 offset1:1
	ds_write2_b32 v144, v98, v99 offset0:2 offset1:3
	ds_write2_b32 v145, v100, v101 offset1:1
	ds_write2_b32 v145, v102, v103 offset0:2 offset1:3
	ds_write2_b32 v146, v104, v105 offset1:1
	ds_write2_b32 v146, v106, v107 offset0:2 offset1:3
	ds_write2_b32 v147, v108, v109 offset1:1
	ds_write2_b32 v147, v110, v111 offset0:2 offset1:3
	ds_write2_b32 v148, v112, v113 offset1:1
	ds_write2_b32 v148, v114, v115 offset0:2 offset1:3
	ds_write2_b32 v149, v116, v117 offset1:1
	ds_write2_b32 v149, v118, v119 offset0:2 offset1:3
	ds_write2_b32 v150, v120, v121 offset1:1
	ds_write2_b32 v150, v122, v123 offset0:2 offset1:3
	ds_write2_b32 v151, v124, v125 offset1:1
	ds_write2_b32 v151, v126, v127 offset0:2 offset1:3
	v_mad_u32_u24 v157, v153, s43, v154
	s_waitcnt lgkmcnt(0)
	ds_read2_b32 v[208:209], v152 offset0:0 offset1:8
	ds_read2_b32 v[210:211], v152 offset0:16 offset1:24
	ds_read2_b32 v[212:213], v152 offset0:33 offset1:41
	ds_read2_b32 v[214:215], v152 offset0:49 offset1:57
	ds_read2_b32 v[216:217], v152 offset0:66 offset1:74
	ds_read2_b32 v[218:219], v152 offset0:82 offset1:90
	ds_read2_b32 v[220:221], v152 offset0:99 offset1:107
	ds_read2_b32 v[222:223], v152 offset0:115 offset1:123
	ds_read2_b32 v[224:225], v152 offset0:132 offset1:140
	ds_read2_b32 v[226:227], v152 offset0:148 offset1:156
	ds_read2_b32 v[228:229], v152 offset0:165 offset1:173
	ds_read2_b32 v[230:231], v152 offset0:181 offset1:189
	ds_read2_b32 v[232:233], v152 offset0:198 offset1:206
	ds_read2_b32 v[234:235], v152 offset0:214 offset1:222
	ds_read2_b32 v[236:237], v152 offset0:231 offset1:239
	ds_read2_b32 v[238:239], v152 offset0:247 offset1:255
	s_waitcnt lgkmcnt(0)
	v_cvt_pk_bf16_f32 v160, v208, v212
	v_cvt_pk_bf16_f32 v161, v216, v220
	v_cvt_pk_bf16_f32 v162, v224, v228
	v_cvt_pk_bf16_f32 v163, v232, v236
	v_cvt_pk_bf16_f32 v164, v209, v213
	v_cvt_pk_bf16_f32 v165, v217, v221
	v_cvt_pk_bf16_f32 v166, v225, v229
	v_cvt_pk_bf16_f32 v167, v233, v237
	v_cvt_pk_bf16_f32 v168, v210, v214
	v_cvt_pk_bf16_f32 v169, v218, v222
	v_cvt_pk_bf16_f32 v170, v226, v230
	v_cvt_pk_bf16_f32 v171, v234, v238
	v_cvt_pk_bf16_f32 v172, v211, v215
	v_cvt_pk_bf16_f32 v173, v219, v223
	v_cvt_pk_bf16_f32 v174, v227, v231
	v_cvt_pk_bf16_f32 v175, v235, v239
	global_store_dwordx4 v157, v[160:163], s[40:41]
	s_add_u32 s40, s40, s42
	s_addc_u32 s41, s41, 0
	global_store_dwordx4 v157, v[164:167], s[40:41]
	s_add_u32 s40, s40, s42
	s_addc_u32 s41, s41, 0
	global_store_dwordx4 v157, v[168:171], s[40:41]
	s_add_u32 s40, s40, s42
	s_addc_u32 s41, s41, 0
	global_store_dwordx4 v157, v[172:175], s[40:41]
	s_add_u32 s40, s40, s42
	s_addc_u32 s41, s41, 0
	s_cmp_lt_i32 s33, 7680
	s_cbranch_scc0 .Ltr_nl1
	s_cmp_lt_i32 s33, 1536
	s_cbranch_scc0 .Ltr_dl11
	s_sub_i32 s0, s33, 0
	s_mul_i32 s1, s0, 683
	s_lshr_b32 s1, s1, 16
	s_mul_i32 s4, s1, 96
	s_sub_i32 s0, s0, s4
	s_lshl_b32 s1, s1, 6
	s_lshl_b32 s0, s0, 5
	s_mul_i32 s4, s1, 3072
	s_add_i32 s4, s4, s0
	s_lshl_b32 s4, s4, 2
	v_readlane_b32 s26, v248, 8
	v_readlane_b32 s27, v248, 9
	s_nop 0
	s_add_u32 s34, s26, s4
	s_addc_u32 s35, s27, 0
	s_mov_b32 s36, 0x18000
	s_mov_b32 s37, 0x3000
	s_and_b32 s1, s1, 0x3ff
	s_lshl_b32 s1, s1, 2
	s_add_u32 s38, s18, s1
	s_addc_u32 s39, s19, 0
	s_branch .Ltr_dxl1

.Ltr_dxl1:
	v_mad_u32_u24 v156, v153, s37, v154
	global_load_dwordx4 v[96:99], v156, s[34:35] nt
	s_add_u32 s34, s34, s36
	s_addc_u32 s35, s35, 0
	global_load_dwordx4 v[100:103], v156, s[34:35] nt
	s_add_u32 s34, s34, s36
	s_addc_u32 s35, s35, 0
	global_load_dwordx4 v[104:107], v156, s[34:35] nt
	s_add_u32 s34, s34, s36
	s_addc_u32 s35, s35, 0
	global_load_dwordx4 v[108:111], v156, s[34:35] nt
	s_add_u32 s34, s34, s36
	s_addc_u32 s35, s35, 0
	global_load_dwordx4 v[112:115], v156, s[34:35] nt
	s_add_u32 s34, s34, s36
	s_addc_u32 s35, s35, 0
	global_load_dwordx4 v[116:119], v156, s[34:35] nt
	s_add_u32 s34, s34, s36
	s_addc_u32 s35, s35, 0
	global_load_dwordx4 v[120:123], v156, s[34:35] nt
	s_add_u32 s34, s34, s36
	s_addc_u32 s35, s35, 0
	global_load_dwordx4 v[124:127], v156, s[34:35] nt
	s_add_u32 s34, s34, s36
	s_addc_u32 s35, s35, 0
	global_load_dword v136, v155, s[38:39]
	global_load_dword v137, v155, s[38:39] offset:32
	global_load_dword v138, v155, s[38:39] offset:64
	global_load_dword v139, v155, s[38:39] offset:96
	global_load_dword v140, v155, s[38:39] offset:128
	global_load_dword v141, v155, s[38:39] offset:160
	global_load_dword v142, v155, s[38:39] offset:192
	global_load_dword v143, v155, s[38:39] offset:224
	s_add_i32 s33, s33, s78
.Ltr_nl1:
	s_add_i32 s31, s31, s78
	s_cmp_lt_i32 s31, 7680
	s_cbranch_scc1 .Ltr_loop
